# v029 with the attention z-gate tile cache-touch moved from the loop exit to tile iteration NT-2 (more lead time, no K/V DMA afterwards)
# baseline (speedup 1.0000x reference)
; DI float bf2f(unsigned short u) { return __uint_as_float((unsigned)u << 16); }
; DI unsigned f2bf(float f) { unsigned u = __float_as_uint(f); return (u + 0x7fffu + ((u >> 16) & 1u)) >> 16; }
; DI int crow(int i, int hh) { return (i & 3) + 8 * (i >> 2) + 4 * hh; }
; DI void attn_unit(Ctx A_, LAS unsigned char* lds, int b, int h, int qb, float lam, int wave, int lane) {
;     ...
;     for (int t = 0; t <= NT; ++t) {
;         asm volatile("s_waitcnt vmcnt(0) lgkmcnt(0)" ::: "memory");
;         __builtin_amdgcn_s_barrier(); asm volatile("" ::: "memory");
;         if (t + 2 < NT) load_tile(lds + ((t + 2) & 3) * BUF, Kg, Vg, (t + 2) * 64, wave, lane);
;     ...
;                 const size_t rw = (size_t)(rowq_e + crow(i, hh_e));
;                 Y_[rw * YLD + C_YA + h_e * 128 + nb * 32 + r_e] = (bf16)f2bf(o[nb][i] * ssq[i] * sn * bf2f(P[rw * PLD + C_ZA + h_e * 128 + nb * 32 + r_e]));
.LBB0_872:
	s_waitcnt vmcnt(0) lgkmcnt(0)
	s_barrier
	s_cmp_lg_u32 s67, s65
	s_cbranch_scc1 .Lattn_tskip
	v_readfirstlane_b32 s98, v0
	s_cmpk_gt_u32 s98, 0xff
	s_cbranch_scc1 .Lattn_tskip
	s_or_b32 s98, s64, s0
	s_mul_hi_u32 s99, s98, 0x5800
	s_mul_i32 s98, s98, 0x5800
	v_readlane_b32 s100, v255, 9
	v_readlane_b32 s101, v255, 10
	v_and_b32_e32 v206, 63, v0
	v_lshrrev_b32_e32 v207, 1, v206
	s_add_u32 s98, s98, s100
	s_addc_u32 s99, s99, s101
	s_lshl_b32 s100, s63, 8
	s_addk_i32 s100, 0x1800
	s_add_u32 s98, s98, s100
	s_addc_u32 s99, s99, 0
	v_mul_u32_u24_e32 v207, 0x5800, v207
	v_and_b32_e32 v206, 1, v206
	v_lshl_or_b32 v206, v206, 7, v207
	s_nop 0
	global_load_dword v207, v206, s[98:99]
